# combined + GEMM loops: LDS stage-base VALU adds folded into ds_read offset immediates (one hoisted base VGPR per loop)
# baseline (speedup 1.0000x reference)
.LBB0_119:
	s_ashr_i32 s21, s20, 31
	s_lshl_b64 s[26:27], s[20:21], 20
	s_add_u32 s26, s14, s26
	s_addc_u32 s27, s15, s27
	s_and_b64 s[28:29], s[28:29], exec
	s_cselect_b32 s21, s27, s43
	s_cselect_b32 s50, s26, s42
	s_add_u32 s40, s40, 0x80080
	s_addc_u32 s41, s41, 0
	s_add_u32 s51, s42, 0x100
	v_mov_b32_e32 v0, 0
	s_addc_u32 s52, s43, 0
	s_mov_b32 s53, -2
	s_waitcnt lgkmcnt(0)
	v_mov_b32_e32 v1, v0
	v_mov_b32_e32 v2, v0
	v_mov_b32_e32 v3, v0
	v_mov_b32_e32 v4, v0
	v_mov_b32_e32 v5, v0
	v_mov_b32_e32 v6, v0
	v_mov_b32_e32 v7, v0
	v_mov_b32_e32 v16, v0
	v_mov_b32_e32 v17, v0
	v_mov_b32_e32 v18, v0
	v_mov_b32_e32 v19, v0
	v_mov_b32_e32 v20, v0
	v_mov_b32_e32 v21, v0
	v_mov_b32_e32 v22, v0
	v_mov_b32_e32 v23, v0
	s_waitcnt vmcnt(0)
	v_mov_b32_e32 v34, v0
	v_mov_b32_e32 v35, v0
	v_mov_b32_e32 v36, v0
	v_mov_b32_e32 v37, v0
	v_mov_b32_e32 v38, v0
	v_mov_b32_e32 v39, v0
	v_mov_b32_e32 v40, v0
	v_mov_b32_e32 v41, v0
	v_mov_b32_e32 v50, v0
	v_mov_b32_e32 v51, v0
	v_mov_b32_e32 v52, v0
	v_mov_b32_e32 v53, v0
	v_mov_b32_e32 v54, v0
	v_mov_b32_e32 v55, v0
	v_mov_b32_e32 v56, v0
	v_mov_b32_e32 v57, v0
	v_mov_b32_e32 v8, v0
	v_mov_b32_e32 v9, v0
	v_mov_b32_e32 v10, v0
	v_mov_b32_e32 v11, v0
	v_mov_b32_e32 v12, v0
	v_mov_b32_e32 v13, v0
	v_mov_b32_e32 v14, v0
	v_mov_b32_e32 v15, v0
	v_mov_b32_e32 v24, v0
	v_mov_b32_e32 v25, v0
	v_mov_b32_e32 v26, v0
	v_mov_b32_e32 v27, v0
	v_mov_b32_e32 v28, v0
	v_mov_b32_e32 v29, v0
	v_mov_b32_e32 v30, v0
	v_mov_b32_e32 v31, v0
	v_mov_b32_e32 v42, v0
	v_mov_b32_e32 v43, v0
	v_mov_b32_e32 v44, v0
	v_mov_b32_e32 v45, v0
	v_mov_b32_e32 v46, v0
	v_mov_b32_e32 v47, v0
	v_mov_b32_e32 v48, v0
	v_mov_b32_e32 v49, v0
	v_mov_b32_e32 v58, v0
	v_mov_b32_e32 v59, v0
	v_mov_b32_e32 v60, v0
	v_mov_b32_e32 v61, v0
	v_mov_b32_e32 v62, v0
	v_mov_b32_e32 v63, v0
	v_mov_b32_e32 v64, v0
	v_mov_b32_e32 v65, v0
	v_mov_b32_e32 v66, v0
	v_mov_b32_e32 v67, v0
	v_mov_b32_e32 v68, v0
	v_mov_b32_e32 v69, v0
	v_mov_b32_e32 v70, v0
	v_mov_b32_e32 v71, v0
	v_mov_b32_e32 v72, v0
	v_mov_b32_e32 v73, v0
	v_mov_b32_e32 v82, v0
	v_mov_b32_e32 v83, v0
	v_mov_b32_e32 v84, v0
	v_mov_b32_e32 v85, v0
	v_mov_b32_e32 v86, v0
	v_mov_b32_e32 v87, v0
	v_mov_b32_e32 v88, v0
	v_mov_b32_e32 v89, v0
	v_mov_b32_e32 v98, v0
	v_mov_b32_e32 v99, v0
	v_mov_b32_e32 v100, v0
	v_mov_b32_e32 v101, v0
	v_mov_b32_e32 v102, v0
	v_mov_b32_e32 v103, v0
	v_mov_b32_e32 v104, v0
	v_mov_b32_e32 v105, v0
	v_mov_b32_e32 v114, v0
	v_mov_b32_e32 v115, v0
	v_mov_b32_e32 v116, v0
	v_mov_b32_e32 v117, v0
	v_mov_b32_e32 v118, v0
	v_mov_b32_e32 v119, v0
	v_mov_b32_e32 v120, v0
	v_mov_b32_e32 v121, v0
	v_mov_b32_e32 v74, v0
	v_mov_b32_e32 v75, v0
	v_mov_b32_e32 v76, v0
	v_mov_b32_e32 v77, v0
	v_mov_b32_e32 v78, v0
	v_mov_b32_e32 v79, v0
	v_mov_b32_e32 v80, v0
	v_mov_b32_e32 v81, v0
	v_mov_b32_e32 v90, v0
	v_mov_b32_e32 v91, v0
	v_mov_b32_e32 v92, v0
	v_mov_b32_e32 v93, v0
	v_mov_b32_e32 v94, v0
	v_mov_b32_e32 v95, v0
	v_mov_b32_e32 v96, v0
	v_mov_b32_e32 v97, v0
	v_mov_b32_e32 v106, v0
	v_mov_b32_e32 v107, v0
	v_mov_b32_e32 v108, v0
	v_mov_b32_e32 v109, v0
	v_mov_b32_e32 v110, v0
	v_mov_b32_e32 v111, v0
	v_mov_b32_e32 v112, v0
	v_mov_b32_e32 v113, v0
	v_mov_b32_e32 v122, v0
	v_mov_b32_e32 v123, v0
	v_mov_b32_e32 v124, v0
	v_mov_b32_e32 v125, v0
	v_mov_b32_e32 v126, v0
	v_mov_b32_e32 v127, v0
	v_mov_b32_e32 v128, v0
	v_mov_b32_e32 v129, v0
	v_add_u32_e32 v226, 0x10000, v212
.LBB0_120:
	s_add_u32 s28, s40, 0xfff80080
	s_addc_u32 s29, s41, -1
	s_add_i32 s54, 0, 0x10000
	s_cmp_eq_u32 s53, 28
	s_cselect_b32 s29, s23, s29
	s_cselect_b32 s28, s22, s28
	s_cselect_b32 s43, s21, s52
	s_cselect_b32 s42, s50, s51
	s_add_i32 s56, 0, 0x14000
	ds_read_b128 v[130:133], v226
	ds_read_b128 v[134:137], v226 offset:1024
	ds_read_b128 v[138:141], v226 offset:2048
	ds_read_b128 v[142:145], v226 offset:3072
	ds_read_b128 v[146:149], v226 offset:16384
	ds_read_b128 v[150:153], v226 offset:17408
	ds_read_b128 v[154:157], v226 offset:18432
	ds_read_b128 v[158:161], v226 offset:19456
	s_add_i32 m0, s24, 0xc000
	ds_read_b128 v[162:165], v213
	ds_read_b128 v[166:169], v213 offset:1024
	ds_read_b128 v[170:173], v213 offset:2048
	ds_read_b128 v[174:177], v213 offset:3072
	ds_read_b128 v[188:191], v213 offset:4096
	ds_read_b128 v[192:195], v213 offset:5120
	ds_read_b128 v[196:199], v213 offset:6144
	ds_read_b128 v[200:203], v213 offset:7168
	global_load_lds_dwordx4 v184, s[40:41]
	s_add_i32 m0, s24, 0xe000
	s_nop 0
	global_load_lds_dwordx4 v186, s[40:41]
	s_waitcnt vmcnt(8)
	s_waitcnt lgkmcnt(0)
	s_barrier
	s_setprio 1
	v_mfma_f32_16x16x32_bf16 v[126:129], v[130:133], v[162:165], v[126:129]
	v_mfma_f32_16x16x32_bf16 v[126:129], v[134:137], v[166:169], v[126:129]
	v_mfma_f32_16x16x32_bf16 v[122:125], v[142:145], v[166:169], v[122:125]
	v_mfma_f32_16x16x32_bf16 v[122:125], v[138:141], v[162:165], v[122:125]
	v_mfma_f32_16x16x32_bf16 v[106:109], v[138:141], v[170:173], v[106:109]
	v_mfma_f32_16x16x32_bf16 v[106:109], v[142:145], v[174:177], v[106:109]
	v_mfma_f32_16x16x32_bf16 v[110:113], v[134:137], v[174:177], v[110:113]
	v_mfma_f32_16x16x32_bf16 v[110:113], v[130:133], v[170:173], v[110:113]
	v_mfma_f32_16x16x32_bf16 v[94:97], v[130:133], v[188:191], v[94:97]
	v_mfma_f32_16x16x32_bf16 v[94:97], v[134:137], v[192:195], v[94:97]
	v_mfma_f32_16x16x32_bf16 v[90:93], v[142:145], v[192:195], v[90:93]
	v_mfma_f32_16x16x32_bf16 v[90:93], v[138:141], v[188:191], v[90:93]
	v_mfma_f32_16x16x32_bf16 v[74:77], v[138:141], v[196:199], v[74:77]
	v_mfma_f32_16x16x32_bf16 v[74:77], v[142:145], v[200:203], v[74:77]
	v_mfma_f32_16x16x32_bf16 v[78:81], v[134:137], v[200:203], v[78:81]
	v_mfma_f32_16x16x32_bf16 v[78:81], v[130:133], v[196:199], v[78:81]
	v_mfma_f32_16x16x32_bf16 v[118:121], v[146:149], v[162:165], v[118:121]
	v_mfma_f32_16x16x32_bf16 v[118:121], v[150:153], v[166:169], v[118:121]
	v_mfma_f32_16x16x32_bf16 v[114:117], v[158:161], v[166:169], v[114:117]
	v_mfma_f32_16x16x32_bf16 v[114:117], v[154:157], v[162:165], v[114:117]
	v_mfma_f32_16x16x32_bf16 v[98:101], v[154:157], v[170:173], v[98:101]
	v_mfma_f32_16x16x32_bf16 v[98:101], v[158:161], v[174:177], v[98:101]
	v_mfma_f32_16x16x32_bf16 v[102:105], v[150:153], v[174:177], v[102:105]
	v_mfma_f32_16x16x32_bf16 v[102:105], v[146:149], v[170:173], v[102:105]
	v_mfma_f32_16x16x32_bf16 v[86:89], v[146:149], v[188:191], v[86:89]
	v_mfma_f32_16x16x32_bf16 v[86:89], v[150:153], v[192:195], v[86:89]
	v_mfma_f32_16x16x32_bf16 v[82:85], v[158:161], v[192:195], v[82:85]
	v_mfma_f32_16x16x32_bf16 v[82:85], v[154:157], v[188:191], v[82:85]
	v_mfma_f32_16x16x32_bf16 v[66:69], v[154:157], v[196:199], v[66:69]
	v_mfma_f32_16x16x32_bf16 v[66:69], v[158:161], v[200:203], v[66:69]
	v_mfma_f32_16x16x32_bf16 v[70:73], v[150:153], v[200:203], v[70:73]
	v_mfma_f32_16x16x32_bf16 v[70:73], v[146:149], v[196:199], v[70:73]
	s_setprio 0
	s_barrier
	s_add_i32 s54, s54, s1
	v_lshl_add_u64 v[204:205], s[42:43], 0, v[32:33]
	s_mov_b32 m0, s54
	ds_read_b128 v[162:165], v213 offset:16384
	ds_read_b128 v[166:169], v213 offset:17408
	ds_read_b128 v[170:173], v213 offset:18432
	ds_read_b128 v[174:177], v213 offset:19456
	ds_read_b128 v[188:191], v213 offset:20480
	ds_read_b128 v[192:195], v213 offset:21504
	ds_read_b128 v[196:199], v213 offset:22528
	ds_read_b128 v[200:203], v213 offset:23552
	global_load_lds_dwordx4 v[204:205], off
	s_add_i32 m0, s54, 0x2000
	s_add_u32 s54, s42, 0x80000
	v_lshl_add_u64 v[206:207], s[42:43], 0, v[182:183]
	s_addc_u32 s55, s43, 0
	s_add_i32 s56, s56, s1
	global_load_lds_dwordx4 v[206:207], off
	s_mov_b32 m0, s56
	v_lshl_add_u64 v[214:215], s[28:29], 0, v[180:181]
	global_load_lds_dwordx4 v32, s[54:55]
	s_add_i32 m0, s56, 0x2000
	s_nop 0
	global_load_lds_dwordx4 v182, s[54:55]
	v_lshl_add_u64 v[208:209], s[28:29], 0, v[178:179]
	s_mov_b32 m0, s24
	s_nop 0
	global_load_lds_dwordx4 v[208:209], off
	s_mov_b32 m0, s25
	s_nop 0
	global_load_lds_dwordx4 v[214:215], off
	s_waitcnt vmcnt(8)
	s_waitcnt lgkmcnt(0)
	s_barrier
	s_setprio 1
	v_mfma_f32_16x16x32_bf16 v[62:65], v[130:133], v[162:165], v[62:65]
	v_mfma_f32_16x16x32_bf16 v[62:65], v[134:137], v[166:169], v[62:65]
	v_mfma_f32_16x16x32_bf16 v[58:61], v[142:145], v[166:169], v[58:61]
	v_mfma_f32_16x16x32_bf16 v[58:61], v[138:141], v[162:165], v[58:61]
	v_mfma_f32_16x16x32_bf16 v[42:45], v[138:141], v[170:173], v[42:45]
	v_mfma_f32_16x16x32_bf16 v[42:45], v[142:145], v[174:177], v[42:45]
	v_mfma_f32_16x16x32_bf16 v[46:49], v[134:137], v[174:177], v[46:49]
	v_mfma_f32_16x16x32_bf16 v[46:49], v[130:133], v[170:173], v[46:49]
	v_mfma_f32_16x16x32_bf16 v[28:31], v[130:133], v[188:191], v[28:31]
	v_mfma_f32_16x16x32_bf16 v[28:31], v[134:137], v[192:195], v[28:31]
	v_mfma_f32_16x16x32_bf16 v[24:27], v[142:145], v[192:195], v[24:27]
	v_mfma_f32_16x16x32_bf16 v[24:27], v[138:141], v[188:191], v[24:27]
	v_mfma_f32_16x16x32_bf16 v[8:11], v[138:141], v[196:199], v[8:11]
	v_mfma_f32_16x16x32_bf16 v[8:11], v[142:145], v[200:203], v[8:11]
	v_mfma_f32_16x16x32_bf16 v[12:15], v[134:137], v[200:203], v[12:15]
	v_mfma_f32_16x16x32_bf16 v[12:15], v[130:133], v[196:199], v[12:15]
	v_mfma_f32_16x16x32_bf16 v[54:57], v[146:149], v[162:165], v[54:57]
	v_mfma_f32_16x16x32_bf16 v[54:57], v[150:153], v[166:169], v[54:57]
	v_mfma_f32_16x16x32_bf16 v[50:53], v[158:161], v[166:169], v[50:53]
	v_mfma_f32_16x16x32_bf16 v[50:53], v[154:157], v[162:165], v[50:53]
	v_mfma_f32_16x16x32_bf16 v[34:37], v[154:157], v[170:173], v[34:37]
	v_mfma_f32_16x16x32_bf16 v[34:37], v[158:161], v[174:177], v[34:37]
	v_mfma_f32_16x16x32_bf16 v[38:41], v[150:153], v[174:177], v[38:41]
	v_mfma_f32_16x16x32_bf16 v[38:41], v[146:149], v[170:173], v[38:41]
	v_mfma_f32_16x16x32_bf16 v[20:23], v[146:149], v[188:191], v[20:23]
	v_mfma_f32_16x16x32_bf16 v[20:23], v[150:153], v[192:195], v[20:23]
	v_mfma_f32_16x16x32_bf16 v[16:19], v[158:161], v[192:195], v[16:19]
	v_mfma_f32_16x16x32_bf16 v[16:19], v[154:157], v[188:191], v[16:19]
	v_mfma_f32_16x16x32_bf16 v[0:3], v[154:157], v[196:199], v[0:3]
	v_mfma_f32_16x16x32_bf16 v[0:3], v[158:161], v[200:203], v[0:3]
	v_mfma_f32_16x16x32_bf16 v[4:7], v[150:153], v[200:203], v[4:7]
	v_mfma_f32_16x16x32_bf16 v[4:7], v[146:149], v[196:199], v[4:7]
	s_setprio 0
	s_barrier
	s_add_i32 s54, 0, 0x18000
	s_add_i32 s55, 0, 0x1c000
	ds_read_b128 v[130:133], v226 offset:32768
	ds_read_b128 v[134:137], v226 offset:33792
	ds_read_b128 v[138:141], v226 offset:34816
	ds_read_b128 v[142:145], v226 offset:35840
	ds_read_b128 v[146:149], v226 offset:49152
	ds_read_b128 v[150:153], v226 offset:50176
	ds_read_b128 v[154:157], v226 offset:51200
	ds_read_b128 v[158:161], v226 offset:52224
	s_add_u32 s28, s28, 0x80000
	s_addc_u32 s29, s29, 0
	s_mov_b32 m0, s33
	ds_read_b128 v[162:165], v213 offset:32768
	ds_read_b128 v[166:169], v213 offset:33792
	ds_read_b128 v[170:173], v213 offset:34816
	ds_read_b128 v[174:177], v213 offset:35840
	ds_read_b128 v[188:191], v213 offset:36864
	ds_read_b128 v[192:195], v213 offset:37888
	ds_read_b128 v[196:199], v213 offset:38912
	ds_read_b128 v[200:203], v213 offset:39936
	global_load_lds_dwordx4 v178, s[28:29]
	s_mov_b32 m0, s36
	s_nop 0
	global_load_lds_dwordx4 v180, s[28:29]
	s_waitcnt vmcnt(8)
	s_waitcnt lgkmcnt(0)
	s_barrier
	s_setprio 1
	v_mfma_f32_16x16x32_bf16 v[126:129], v[130:133], v[162:165], v[126:129]
	v_mfma_f32_16x16x32_bf16 v[126:129], v[134:137], v[166:169], v[126:129]
	v_mfma_f32_16x16x32_bf16 v[122:125], v[142:145], v[166:169], v[122:125]
	v_mfma_f32_16x16x32_bf16 v[122:125], v[138:141], v[162:165], v[122:125]
	v_mfma_f32_16x16x32_bf16 v[106:109], v[138:141], v[170:173], v[106:109]
	v_mfma_f32_16x16x32_bf16 v[106:109], v[142:145], v[174:177], v[106:109]
	v_mfma_f32_16x16x32_bf16 v[110:113], v[134:137], v[174:177], v[110:113]
	v_mfma_f32_16x16x32_bf16 v[110:113], v[130:133], v[170:173], v[110:113]
	v_mfma_f32_16x16x32_bf16 v[94:97], v[130:133], v[188:191], v[94:97]
	v_mfma_f32_16x16x32_bf16 v[94:97], v[134:137], v[192:195], v[94:97]
	v_mfma_f32_16x16x32_bf16 v[90:93], v[142:145], v[192:195], v[90:93]
	v_mfma_f32_16x16x32_bf16 v[90:93], v[138:141], v[188:191], v[90:93]
	v_mfma_f32_16x16x32_bf16 v[74:77], v[138:141], v[196:199], v[74:77]
	v_mfma_f32_16x16x32_bf16 v[74:77], v[142:145], v[200:203], v[74:77]
	v_mfma_f32_16x16x32_bf16 v[78:81], v[134:137], v[200:203], v[78:81]
	v_mfma_f32_16x16x32_bf16 v[78:81], v[130:133], v[196:199], v[78:81]
	v_mfma_f32_16x16x32_bf16 v[118:121], v[146:149], v[162:165], v[118:121]
	v_mfma_f32_16x16x32_bf16 v[118:121], v[150:153], v[166:169], v[118:121]
	v_mfma_f32_16x16x32_bf16 v[114:117], v[158:161], v[166:169], v[114:117]
	v_mfma_f32_16x16x32_bf16 v[114:117], v[154:157], v[162:165], v[114:117]
	v_mfma_f32_16x16x32_bf16 v[98:101], v[154:157], v[170:173], v[98:101]
	v_mfma_f32_16x16x32_bf16 v[98:101], v[158:161], v[174:177], v[98:101]
	v_mfma_f32_16x16x32_bf16 v[102:105], v[150:153], v[174:177], v[102:105]
	v_mfma_f32_16x16x32_bf16 v[102:105], v[146:149], v[170:173], v[102:105]
	v_mfma_f32_16x16x32_bf16 v[86:89], v[146:149], v[188:191], v[86:89]
	v_mfma_f32_16x16x32_bf16 v[86:89], v[150:153], v[192:195], v[86:89]
	v_mfma_f32_16x16x32_bf16 v[82:85], v[158:161], v[192:195], v[82:85]
	v_mfma_f32_16x16x32_bf16 v[82:85], v[154:157], v[188:191], v[82:85]
	v_mfma_f32_16x16x32_bf16 v[66:69], v[154:157], v[196:199], v[66:69]
	v_mfma_f32_16x16x32_bf16 v[66:69], v[158:161], v[200:203], v[66:69]
	v_mfma_f32_16x16x32_bf16 v[70:73], v[150:153], v[200:203], v[70:73]
	v_mfma_f32_16x16x32_bf16 v[70:73], v[146:149], v[196:199], v[70:73]
	s_setprio 0
	s_barrier
	s_add_i32 s28, s54, s1
	v_lshl_add_u64 v[204:205], v[204:205], 0, s[34:35]
	s_mov_b32 m0, s28
	ds_read_b128 v[162:165], v213 offset:49152
	ds_read_b128 v[166:169], v213 offset:50176
	ds_read_b128 v[170:173], v213 offset:51200
	ds_read_b128 v[174:177], v213 offset:52224
	ds_read_b128 v[188:191], v213 offset:53248
	ds_read_b128 v[192:195], v213 offset:54272
	ds_read_b128 v[196:199], v213 offset:55296
	ds_read_b128 v[200:203], v213 offset:56320
	global_load_lds_dwordx4 v[204:205], off
	s_add_i32 m0, s28, 0x2000
	s_add_u32 s28, s42, 0x80080
	v_lshl_add_u64 v[204:205], v[206:207], 0, s[34:35]
	s_addc_u32 s29, s43, 0
	s_add_i32 s42, s55, s1
	global_load_lds_dwordx4 v[204:205], off
	s_mov_b32 m0, s42
	s_nop 0
	global_load_lds_dwordx4 v32, s[28:29]
	s_add_i32 m0, s42, 0x2000
	s_nop 0
	global_load_lds_dwordx4 v182, s[28:29]
	v_lshl_add_u64 v[204:205], v[208:209], 0, s[34:35]
	s_mov_b32 m0, s44
	s_nop 0
	global_load_lds_dwordx4 v[204:205], off
	v_lshl_add_u64 v[204:205], v[214:215], 0, s[34:35]
	s_mov_b32 m0, s45
	s_nop 0
	global_load_lds_dwordx4 v[204:205], off
	s_waitcnt vmcnt(8)
	s_waitcnt lgkmcnt(0)
	s_barrier
	s_setprio 1
	v_mfma_f32_16x16x32_bf16 v[62:65], v[130:133], v[162:165], v[62:65]
	v_mfma_f32_16x16x32_bf16 v[62:65], v[134:137], v[166:169], v[62:65]
	v_mfma_f32_16x16x32_bf16 v[58:61], v[142:145], v[166:169], v[58:61]
	v_mfma_f32_16x16x32_bf16 v[58:61], v[138:141], v[162:165], v[58:61]
	v_mfma_f32_16x16x32_bf16 v[42:45], v[138:141], v[170:173], v[42:45]
	v_mfma_f32_16x16x32_bf16 v[42:45], v[142:145], v[174:177], v[42:45]
	v_mfma_f32_16x16x32_bf16 v[46:49], v[134:137], v[174:177], v[46:49]
	v_mfma_f32_16x16x32_bf16 v[46:49], v[130:133], v[170:173], v[46:49]
	v_mfma_f32_16x16x32_bf16 v[28:31], v[130:133], v[188:191], v[28:31]
	v_mfma_f32_16x16x32_bf16 v[28:31], v[134:137], v[192:195], v[28:31]
	v_mfma_f32_16x16x32_bf16 v[24:27], v[142:145], v[192:195], v[24:27]
	v_mfma_f32_16x16x32_bf16 v[24:27], v[138:141], v[188:191], v[24:27]
	v_mfma_f32_16x16x32_bf16 v[8:11], v[138:141], v[196:199], v[8:11]
	v_mfma_f32_16x16x32_bf16 v[8:11], v[142:145], v[200:203], v[8:11]
	v_mfma_f32_16x16x32_bf16 v[12:15], v[134:137], v[200:203], v[12:15]
	v_mfma_f32_16x16x32_bf16 v[12:15], v[130:133], v[196:199], v[12:15]
	v_mfma_f32_16x16x32_bf16 v[54:57], v[146:149], v[162:165], v[54:57]
	v_mfma_f32_16x16x32_bf16 v[54:57], v[150:153], v[166:169], v[54:57]
	v_mfma_f32_16x16x32_bf16 v[50:53], v[158:161], v[166:169], v[50:53]
	v_mfma_f32_16x16x32_bf16 v[50:53], v[154:157], v[162:165], v[50:53]
	v_mfma_f32_16x16x32_bf16 v[34:37], v[154:157], v[170:173], v[34:37]
	v_mfma_f32_16x16x32_bf16 v[34:37], v[158:161], v[174:177], v[34:37]
	v_mfma_f32_16x16x32_bf16 v[38:41], v[150:153], v[174:177], v[38:41]
	v_mfma_f32_16x16x32_bf16 v[38:41], v[146:149], v[170:173], v[38:41]
	v_mfma_f32_16x16x32_bf16 v[20:23], v[146:149], v[188:191], v[20:23]
	v_mfma_f32_16x16x32_bf16 v[20:23], v[150:153], v[192:195], v[20:23]
	v_mfma_f32_16x16x32_bf16 v[16:19], v[158:161], v[192:195], v[16:19]
	v_mfma_f32_16x16x32_bf16 v[16:19], v[154:157], v[188:191], v[16:19]
	v_mfma_f32_16x16x32_bf16 v[0:3], v[154:157], v[196:199], v[0:3]
	v_mfma_f32_16x16x32_bf16 v[0:3], v[158:161], v[200:203], v[0:3]
	v_mfma_f32_16x16x32_bf16 v[4:7], v[150:153], v[200:203], v[4:7]
	v_mfma_f32_16x16x32_bf16 v[4:7], v[146:149], v[196:199], v[4:7]
	s_setprio 0
	s_barrier
	s_add_i32 s53, s53, 2
	s_add_u32 s40, s40, 0x100
	s_addc_u32 s41, s41, 0
	s_add_u32 s51, s51, 0x100
	s_addc_u32 s52, s52, 0
	s_cmp_gt_u32 s53, 29
	s_cbranch_scc0 .LBB0_120
	s_and_b64 vcc, exec, s[18:19]
	s_cbranch_vccz .LBB0_123
	s_barrier

.LBB0_684:
	s_add_u32 s52, s40, 0x100
	s_addc_u32 s53, s41, 0
	s_ashr_i32 s23, s22, 31
	s_lshl_b64 s[30:31], s[22:23], 20
	s_add_u32 s30, s10, s30
	s_addc_u32 s31, s11, s31
	s_and_b64 s[28:29], s[28:29], exec
	s_cselect_b32 s23, s31, s41
	s_cselect_b32 s54, s30, s40
	s_add_u32 s28, s16, 0x80080
	s_addc_u32 s29, s17, 0
	v_lshl_add_u64 v[130:131], s[28:29], 0, v[176:177]
	v_lshl_add_u64 v[132:133], s[28:29], 0, v[178:179]
	s_mov_b32 s55, -2
	s_mov_b64 s[40:41], 0
	v_add_u32_e32 v224, 0x10000, v190
.LBB0_685:
	s_add_u32 s28, s16, s40
	s_addc_u32 s29, s17, s41
	s_add_u32 s28, s28, 0x100
	s_addc_u32 s29, s29, 0
	s_add_u32 s42, s52, s40
	s_addc_u32 s43, s53, s41
	s_add_i32 s56, 0, 0x10000
	s_cmpk_eq_i32 s40, 0xf00
	s_cselect_b32 s29, s39, s29
	s_cselect_b32 s28, s38, s28
	s_cselect_b32 s43, s23, s43
	s_cselect_b32 s42, s54, s42
	s_add_i32 s58, 0, 0x14000
	ds_read_b128 v[134:137], v224
	ds_read_b128 v[138:141], v224 offset:1024
	ds_read_b128 v[142:145], v224 offset:2048
	ds_read_b128 v[146:149], v224 offset:3072
	ds_read_b128 v[150:153], v224 offset:16384
	ds_read_b128 v[154:157], v224 offset:17408
	ds_read_b128 v[158:161], v224 offset:18432
	ds_read_b128 v[162:165], v224 offset:19456
	v_lshl_add_u64 v[212:213], v[130:131], 0, s[40:41]
	s_add_i32 m0, s24, 0xc000
	ds_read_b128 v[166:169], v191
	ds_read_b128 v[180:183], v191 offset:1024
	ds_read_b128 v[184:187], v191 offset:2048
	ds_read_b128 v[192:195], v191 offset:3072
	ds_read_b128 v[196:199], v191 offset:4096
	ds_read_b128 v[200:203], v191 offset:5120
	ds_read_b128 v[204:207], v191 offset:6144
	ds_read_b128 v[208:211], v191 offset:7168
	global_load_lds_dwordx4 v[212:213], off
	v_lshl_add_u64 v[212:213], v[132:133], 0, s[40:41]
	s_add_i32 m0, s24, 0xe000
	s_nop 0
	global_load_lds_dwordx4 v[212:213], off
	s_waitcnt vmcnt(8)
	s_waitcnt lgkmcnt(0)
	s_barrier
	s_setprio 1
	v_mfma_f32_16x16x32_bf16 v[82:85], v[134:137], v[166:169], v[82:85]
	v_mfma_f32_16x16x32_bf16 v[82:85], v[138:141], v[180:183], v[82:85]
	v_mfma_f32_16x16x32_bf16 v[78:81], v[146:149], v[180:183], v[78:81]
	v_mfma_f32_16x16x32_bf16 v[78:81], v[142:145], v[166:169], v[78:81]
	v_mfma_f32_16x16x32_bf16 v[70:73], v[142:145], v[184:187], v[70:73]
	v_mfma_f32_16x16x32_bf16 v[70:73], v[146:149], v[192:195], v[70:73]
	v_mfma_f32_16x16x32_bf16 v[74:77], v[138:141], v[192:195], v[74:77]
	v_mfma_f32_16x16x32_bf16 v[74:77], v[134:137], v[184:187], v[74:77]
	v_mfma_f32_16x16x32_bf16 v[66:69], v[134:137], v[196:199], v[66:69]
	v_mfma_f32_16x16x32_bf16 v[66:69], v[138:141], v[200:203], v[66:69]
	v_mfma_f32_16x16x32_bf16 v[62:65], v[146:149], v[200:203], v[62:65]
	v_mfma_f32_16x16x32_bf16 v[62:65], v[142:145], v[196:199], v[62:65]
	v_mfma_f32_16x16x32_bf16 v[54:57], v[142:145], v[204:207], v[54:57]
	v_mfma_f32_16x16x32_bf16 v[54:57], v[146:149], v[208:211], v[54:57]
	v_mfma_f32_16x16x32_bf16 v[58:61], v[138:141], v[208:211], v[58:61]
	v_mfma_f32_16x16x32_bf16 v[58:61], v[134:137], v[204:207], v[58:61]
	v_mfma_f32_16x16x32_bf16 v[50:53], v[150:153], v[166:169], v[50:53]
	v_mfma_f32_16x16x32_bf16 v[50:53], v[154:157], v[180:183], v[50:53]
	v_mfma_f32_16x16x32_bf16 v[46:49], v[162:165], v[180:183], v[46:49]
	v_mfma_f32_16x16x32_bf16 v[46:49], v[158:161], v[166:169], v[46:49]
	v_mfma_f32_16x16x32_bf16 v[38:41], v[158:161], v[184:187], v[38:41]
	v_mfma_f32_16x16x32_bf16 v[38:41], v[162:165], v[192:195], v[38:41]
	v_mfma_f32_16x16x32_bf16 v[42:45], v[154:157], v[192:195], v[42:45]
	v_mfma_f32_16x16x32_bf16 v[42:45], v[150:153], v[184:187], v[42:45]
	v_mfma_f32_16x16x32_bf16 v[34:37], v[150:153], v[196:199], v[34:37]
	v_mfma_f32_16x16x32_bf16 v[34:37], v[154:157], v[200:203], v[34:37]
	v_mfma_f32_16x16x32_bf16 v[28:31], v[162:165], v[200:203], v[28:31]
	v_mfma_f32_16x16x32_bf16 v[28:31], v[158:161], v[196:199], v[28:31]
	v_mfma_f32_16x16x32_bf16 v[20:23], v[158:161], v[204:207], v[20:23]
	v_mfma_f32_16x16x32_bf16 v[20:23], v[162:165], v[208:211], v[20:23]
	v_mfma_f32_16x16x32_bf16 v[24:27], v[154:157], v[208:211], v[24:27]
	v_mfma_f32_16x16x32_bf16 v[24:27], v[150:153], v[204:207], v[24:27]
	s_setprio 0
	s_barrier
	s_add_i32 s56, s56, s13
	v_lshl_add_u64 v[212:213], s[42:43], 0, v[32:33]
	s_mov_b32 m0, s56
	ds_read_b128 v[166:169], v191 offset:16384
	ds_read_b128 v[180:183], v191 offset:17408
	ds_read_b128 v[184:187], v191 offset:18432
	ds_read_b128 v[192:195], v191 offset:19456
	ds_read_b128 v[196:199], v191 offset:20480
	ds_read_b128 v[200:203], v191 offset:21504
	ds_read_b128 v[204:207], v191 offset:22528
	ds_read_b128 v[208:211], v191 offset:23552
	global_load_lds_dwordx4 v[212:213], off
	s_add_i32 m0, s56, 0x2000
	s_add_u32 s56, s42, 0x80000
	v_lshl_add_u64 v[214:215], s[42:43], 0, v[174:175]
	s_addc_u32 s57, s43, 0
	s_add_i32 s58, s58, s13
	global_load_lds_dwordx4 v[214:215], off
	s_mov_b32 m0, s58
	v_lshl_add_u64 v[220:221], s[28:29], 0, v[172:173]
	global_load_lds_dwordx4 v32, s[56:57]
	s_add_i32 m0, s58, 0x2000
	s_nop 0
	global_load_lds_dwordx4 v174, s[56:57]
	v_lshl_add_u64 v[216:217], s[28:29], 0, v[170:171]
	s_mov_b32 m0, s24
	s_nop 0
	global_load_lds_dwordx4 v[216:217], off
	s_mov_b32 m0, s25
	s_nop 0
	global_load_lds_dwordx4 v[220:221], off
	s_waitcnt vmcnt(8)
	s_waitcnt lgkmcnt(0)
	s_barrier
	s_setprio 1
	v_mfma_f32_16x16x32_bf16 v[16:19], v[134:137], v[166:169], v[16:19]
	v_mfma_f32_16x16x32_bf16 v[16:19], v[138:141], v[180:183], v[16:19]
	v_mfma_f32_16x16x32_bf16 v[12:15], v[146:149], v[180:183], v[12:15]
	v_mfma_f32_16x16x32_bf16 v[12:15], v[142:145], v[166:169], v[12:15]
	v_mfma_f32_16x16x32_bf16 v[4:7], v[142:145], v[184:187], v[4:7]
	v_mfma_f32_16x16x32_bf16 v[4:7], v[146:149], v[192:195], v[4:7]
	v_mfma_f32_16x16x32_bf16 v[8:11], v[138:141], v[192:195], v[8:11]
	v_mfma_f32_16x16x32_bf16 v[8:11], v[134:137], v[184:187], v[8:11]
	v_mfma_f32_16x16x32_bf16 v[0:3], v[134:137], v[196:199], v[0:3]
	v_mfma_f32_16x16x32_bf16 v[0:3], v[138:141], v[200:203], v[0:3]
	v_mfma_f32_16x16x32_bf16 v[86:89], v[146:149], v[200:203], v[86:89]
	v_mfma_f32_16x16x32_bf16 v[86:89], v[142:145], v[196:199], v[86:89]
	v_mfma_f32_16x16x32_bf16 v[94:97], v[142:145], v[204:207], v[94:97]
	v_mfma_f32_16x16x32_bf16 v[94:97], v[146:149], v[208:211], v[94:97]
	v_mfma_f32_16x16x32_bf16 v[90:93], v[138:141], v[208:211], v[90:93]
	v_mfma_f32_16x16x32_bf16 v[90:93], v[134:137], v[204:207], v[90:93]
	v_mfma_f32_16x16x32_bf16 v[98:101], v[150:153], v[166:169], v[98:101]
	v_mfma_f32_16x16x32_bf16 v[98:101], v[154:157], v[180:183], v[98:101]
	v_mfma_f32_16x16x32_bf16 v[102:105], v[162:165], v[180:183], v[102:105]
	v_mfma_f32_16x16x32_bf16 v[102:105], v[158:161], v[166:169], v[102:105]
	v_mfma_f32_16x16x32_bf16 v[110:113], v[158:161], v[184:187], v[110:113]
	v_mfma_f32_16x16x32_bf16 v[110:113], v[162:165], v[192:195], v[110:113]
	v_mfma_f32_16x16x32_bf16 v[106:109], v[154:157], v[192:195], v[106:109]
	v_mfma_f32_16x16x32_bf16 v[106:109], v[150:153], v[184:187], v[106:109]
	v_mfma_f32_16x16x32_bf16 v[114:117], v[150:153], v[196:199], v[114:117]
	v_mfma_f32_16x16x32_bf16 v[114:117], v[154:157], v[200:203], v[114:117]
	v_mfma_f32_16x16x32_bf16 v[118:121], v[162:165], v[200:203], v[118:121]
	v_mfma_f32_16x16x32_bf16 v[118:121], v[158:161], v[196:199], v[118:121]
	v_mfma_f32_16x16x32_bf16 v[126:129], v[158:161], v[204:207], v[126:129]
	v_mfma_f32_16x16x32_bf16 v[126:129], v[162:165], v[208:211], v[126:129]
	v_mfma_f32_16x16x32_bf16 v[122:125], v[154:157], v[208:211], v[122:125]
	v_mfma_f32_16x16x32_bf16 v[122:125], v[150:153], v[204:207], v[122:125]
	s_setprio 0
	s_barrier
	s_add_i32 s56, 0, 0x18000
	s_add_i32 s57, 0, 0x1c000
	ds_read_b128 v[134:137], v224 offset:32768
	ds_read_b128 v[138:141], v224 offset:33792
	ds_read_b128 v[142:145], v224 offset:34816
	ds_read_b128 v[146:149], v224 offset:35840
	ds_read_b128 v[150:153], v224 offset:49152
	ds_read_b128 v[154:157], v224 offset:50176
	ds_read_b128 v[158:161], v224 offset:51200
	ds_read_b128 v[162:165], v224 offset:52224
	s_add_u32 s28, s28, 0x80000
	s_addc_u32 s29, s29, 0
	s_mov_b32 m0, s33
	ds_read_b128 v[166:169], v191 offset:32768
	ds_read_b128 v[180:183], v191 offset:33792
	ds_read_b128 v[184:187], v191 offset:34816
	ds_read_b128 v[192:195], v191 offset:35840
	ds_read_b128 v[196:199], v191 offset:36864
	ds_read_b128 v[200:203], v191 offset:37888
	ds_read_b128 v[204:207], v191 offset:38912
	ds_read_b128 v[208:211], v191 offset:39936
	global_load_lds_dwordx4 v170, s[28:29]
	s_mov_b32 m0, s36
	s_nop 0
	global_load_lds_dwordx4 v172, s[28:29]
	s_waitcnt vmcnt(8)
	s_waitcnt lgkmcnt(0)
	s_barrier
	s_setprio 1
	v_mfma_f32_16x16x32_bf16 v[82:85], v[134:137], v[166:169], v[82:85]
	v_mfma_f32_16x16x32_bf16 v[82:85], v[138:141], v[180:183], v[82:85]
	v_mfma_f32_16x16x32_bf16 v[78:81], v[146:149], v[180:183], v[78:81]
	v_mfma_f32_16x16x32_bf16 v[78:81], v[142:145], v[166:169], v[78:81]
	v_mfma_f32_16x16x32_bf16 v[70:73], v[142:145], v[184:187], v[70:73]
	v_mfma_f32_16x16x32_bf16 v[70:73], v[146:149], v[192:195], v[70:73]
	v_mfma_f32_16x16x32_bf16 v[74:77], v[138:141], v[192:195], v[74:77]
	v_mfma_f32_16x16x32_bf16 v[74:77], v[134:137], v[184:187], v[74:77]
	v_mfma_f32_16x16x32_bf16 v[66:69], v[134:137], v[196:199], v[66:69]
	v_mfma_f32_16x16x32_bf16 v[66:69], v[138:141], v[200:203], v[66:69]
	v_mfma_f32_16x16x32_bf16 v[62:65], v[146:149], v[200:203], v[62:65]
	v_mfma_f32_16x16x32_bf16 v[62:65], v[142:145], v[196:199], v[62:65]
	v_mfma_f32_16x16x32_bf16 v[54:57], v[142:145], v[204:207], v[54:57]
	v_mfma_f32_16x16x32_bf16 v[54:57], v[146:149], v[208:211], v[54:57]
	v_mfma_f32_16x16x32_bf16 v[58:61], v[138:141], v[208:211], v[58:61]
	v_mfma_f32_16x16x32_bf16 v[58:61], v[134:137], v[204:207], v[58:61]
	v_mfma_f32_16x16x32_bf16 v[50:53], v[150:153], v[166:169], v[50:53]
	v_mfma_f32_16x16x32_bf16 v[50:53], v[154:157], v[180:183], v[50:53]
	v_mfma_f32_16x16x32_bf16 v[46:49], v[162:165], v[180:183], v[46:49]
	v_mfma_f32_16x16x32_bf16 v[46:49], v[158:161], v[166:169], v[46:49]
	v_mfma_f32_16x16x32_bf16 v[38:41], v[158:161], v[184:187], v[38:41]
	v_mfma_f32_16x16x32_bf16 v[38:41], v[162:165], v[192:195], v[38:41]
	v_mfma_f32_16x16x32_bf16 v[42:45], v[154:157], v[192:195], v[42:45]
	v_mfma_f32_16x16x32_bf16 v[42:45], v[150:153], v[184:187], v[42:45]
	v_mfma_f32_16x16x32_bf16 v[34:37], v[150:153], v[196:199], v[34:37]
	v_mfma_f32_16x16x32_bf16 v[34:37], v[154:157], v[200:203], v[34:37]
	v_mfma_f32_16x16x32_bf16 v[28:31], v[162:165], v[200:203], v[28:31]
	v_mfma_f32_16x16x32_bf16 v[28:31], v[158:161], v[196:199], v[28:31]
	v_mfma_f32_16x16x32_bf16 v[20:23], v[158:161], v[204:207], v[20:23]
	v_mfma_f32_16x16x32_bf16 v[20:23], v[162:165], v[208:211], v[20:23]
	v_mfma_f32_16x16x32_bf16 v[24:27], v[154:157], v[208:211], v[24:27]
	v_mfma_f32_16x16x32_bf16 v[24:27], v[150:153], v[204:207], v[24:27]
	s_setprio 0
	s_barrier
	s_add_i32 s28, s56, s13
	v_lshl_add_u64 v[212:213], v[212:213], 0, s[34:35]
	s_mov_b32 m0, s28
	ds_read_b128 v[166:169], v191 offset:49152
	ds_read_b128 v[180:183], v191 offset:50176
	ds_read_b128 v[184:187], v191 offset:51200
	ds_read_b128 v[192:195], v191 offset:52224
	ds_read_b128 v[196:199], v191 offset:53248
	ds_read_b128 v[200:203], v191 offset:54272
	ds_read_b128 v[204:207], v191 offset:55296
	ds_read_b128 v[208:211], v191 offset:56320
	global_load_lds_dwordx4 v[212:213], off
	s_add_i32 m0, s28, 0x2000
	s_add_u32 s28, s42, 0x80080
	v_lshl_add_u64 v[212:213], v[214:215], 0, s[34:35]
	s_addc_u32 s29, s43, 0
	s_add_i32 s42, s57, s13
	global_load_lds_dwordx4 v[212:213], off
	s_mov_b32 m0, s42
	s_nop 0
	global_load_lds_dwordx4 v32, s[28:29]
	s_add_i32 m0, s42, 0x2000
	s_nop 0
	global_load_lds_dwordx4 v174, s[28:29]
	v_lshl_add_u64 v[212:213], v[216:217], 0, s[34:35]
	s_mov_b32 m0, s45
	s_nop 0
	global_load_lds_dwordx4 v[212:213], off
	v_lshl_add_u64 v[212:213], v[220:221], 0, s[34:35]
	s_mov_b32 m0, s46
	s_nop 0
	global_load_lds_dwordx4 v[212:213], off
	s_waitcnt vmcnt(8)
	s_waitcnt lgkmcnt(0)
	s_barrier
	s_setprio 1
	v_mfma_f32_16x16x32_bf16 v[16:19], v[134:137], v[166:169], v[16:19]
	v_mfma_f32_16x16x32_bf16 v[16:19], v[138:141], v[180:183], v[16:19]
	v_mfma_f32_16x16x32_bf16 v[12:15], v[146:149], v[180:183], v[12:15]
	v_mfma_f32_16x16x32_bf16 v[12:15], v[142:145], v[166:169], v[12:15]
	v_mfma_f32_16x16x32_bf16 v[4:7], v[142:145], v[184:187], v[4:7]
	v_mfma_f32_16x16x32_bf16 v[4:7], v[146:149], v[192:195], v[4:7]
	v_mfma_f32_16x16x32_bf16 v[8:11], v[138:141], v[192:195], v[8:11]
	v_mfma_f32_16x16x32_bf16 v[8:11], v[134:137], v[184:187], v[8:11]
	v_mfma_f32_16x16x32_bf16 v[0:3], v[134:137], v[196:199], v[0:3]
	v_mfma_f32_16x16x32_bf16 v[0:3], v[138:141], v[200:203], v[0:3]
	v_mfma_f32_16x16x32_bf16 v[86:89], v[146:149], v[200:203], v[86:89]
	v_mfma_f32_16x16x32_bf16 v[86:89], v[142:145], v[196:199], v[86:89]
	v_mfma_f32_16x16x32_bf16 v[94:97], v[142:145], v[204:207], v[94:97]
	v_mfma_f32_16x16x32_bf16 v[94:97], v[146:149], v[208:211], v[94:97]
	v_mfma_f32_16x16x32_bf16 v[90:93], v[138:141], v[208:211], v[90:93]
	v_mfma_f32_16x16x32_bf16 v[90:93], v[134:137], v[204:207], v[90:93]
	v_mfma_f32_16x16x32_bf16 v[98:101], v[150:153], v[166:169], v[98:101]
	v_mfma_f32_16x16x32_bf16 v[98:101], v[154:157], v[180:183], v[98:101]
	v_mfma_f32_16x16x32_bf16 v[102:105], v[162:165], v[180:183], v[102:105]
	v_mfma_f32_16x16x32_bf16 v[102:105], v[158:161], v[166:169], v[102:105]
	v_mfma_f32_16x16x32_bf16 v[110:113], v[158:161], v[184:187], v[110:113]
	v_mfma_f32_16x16x32_bf16 v[110:113], v[162:165], v[192:195], v[110:113]
	v_mfma_f32_16x16x32_bf16 v[106:109], v[154:157], v[192:195], v[106:109]
	v_mfma_f32_16x16x32_bf16 v[106:109], v[150:153], v[184:187], v[106:109]
	v_mfma_f32_16x16x32_bf16 v[114:117], v[150:153], v[196:199], v[114:117]
	v_mfma_f32_16x16x32_bf16 v[114:117], v[154:157], v[200:203], v[114:117]
	v_mfma_f32_16x16x32_bf16 v[118:121], v[162:165], v[200:203], v[118:121]
	v_mfma_f32_16x16x32_bf16 v[118:121], v[158:161], v[196:199], v[118:121]
	v_mfma_f32_16x16x32_bf16 v[126:129], v[158:161], v[204:207], v[126:129]
	v_mfma_f32_16x16x32_bf16 v[126:129], v[162:165], v[208:211], v[126:129]
	v_mfma_f32_16x16x32_bf16 v[122:125], v[154:157], v[208:211], v[122:125]
	v_mfma_f32_16x16x32_bf16 v[122:125], v[150:153], v[204:207], v[122:125]
	s_setprio 0
	s_barrier
	s_add_i32 s55, s55, 2
	s_add_u32 s40, s40, 0x100
	s_addc_u32 s41, s41, 0
	s_cmp_gt_u32 s55, 29
	s_cbranch_scc0 .LBB0_685
	s_and_b64 vcc, exec, s[18:19]
	s_cbranch_vccz .LBB0_688
	s_barrier

.LBB0_754:
	s_add_u32 s33, s6, 0x100
	v_mov_b32_e32 v0, 0
	s_addc_u32 s50, s7, 0
	s_mov_b32 s51, -2
	s_waitcnt lgkmcnt(0)
	v_mov_b32_e32 v1, v0
	v_mov_b32_e32 v2, v0
	v_mov_b32_e32 v3, v0
	v_mov_b32_e32 v4, v0
	v_mov_b32_e32 v5, v0
	v_mov_b32_e32 v6, v0
	v_mov_b32_e32 v7, v0
	v_mov_b32_e32 v16, v0
	v_mov_b32_e32 v17, v0
	v_mov_b32_e32 v18, v0
	v_mov_b32_e32 v19, v0
	v_mov_b32_e32 v20, v0
	v_mov_b32_e32 v21, v0
	v_mov_b32_e32 v22, v0
	v_mov_b32_e32 v23, v0
	s_waitcnt vmcnt(0)
	v_mov_b32_e32 v34, v0
	v_mov_b32_e32 v35, v0
	v_mov_b32_e32 v36, v0
	v_mov_b32_e32 v37, v0
	v_mov_b32_e32 v38, v0
	v_mov_b32_e32 v39, v0
	v_mov_b32_e32 v40, v0
	v_mov_b32_e32 v41, v0
	v_mov_b32_e32 v50, v0
	v_mov_b32_e32 v51, v0
	v_mov_b32_e32 v52, v0
	v_mov_b32_e32 v53, v0
	v_mov_b32_e32 v54, v0
	v_mov_b32_e32 v55, v0
	v_mov_b32_e32 v56, v0
	v_mov_b32_e32 v57, v0
	v_mov_b32_e32 v8, v0
	v_mov_b32_e32 v9, v0
	v_mov_b32_e32 v10, v0
	v_mov_b32_e32 v11, v0
	v_mov_b32_e32 v12, v0
	v_mov_b32_e32 v13, v0
	v_mov_b32_e32 v14, v0
	v_mov_b32_e32 v15, v0
	v_mov_b32_e32 v24, v0
	v_mov_b32_e32 v25, v0
	v_mov_b32_e32 v26, v0
	v_mov_b32_e32 v27, v0
	v_mov_b32_e32 v28, v0
	v_mov_b32_e32 v29, v0
	v_mov_b32_e32 v30, v0
	v_mov_b32_e32 v31, v0
	v_mov_b32_e32 v42, v0
	v_mov_b32_e32 v43, v0
	v_mov_b32_e32 v44, v0
	v_mov_b32_e32 v45, v0
	v_mov_b32_e32 v46, v0
	v_mov_b32_e32 v47, v0
	v_mov_b32_e32 v48, v0
	v_mov_b32_e32 v49, v0
	v_mov_b32_e32 v58, v0
	v_mov_b32_e32 v59, v0
	v_mov_b32_e32 v60, v0
	v_mov_b32_e32 v61, v0
	v_mov_b32_e32 v62, v0
	v_mov_b32_e32 v63, v0
	v_mov_b32_e32 v64, v0
	v_mov_b32_e32 v65, v0
	v_mov_b32_e32 v66, v0
	v_mov_b32_e32 v67, v0
	v_mov_b32_e32 v68, v0
	v_mov_b32_e32 v69, v0
	v_mov_b32_e32 v70, v0
	v_mov_b32_e32 v71, v0
	v_mov_b32_e32 v72, v0
	v_mov_b32_e32 v73, v0
	v_mov_b32_e32 v82, v0
	v_mov_b32_e32 v83, v0
	v_mov_b32_e32 v84, v0
	v_mov_b32_e32 v85, v0
	v_mov_b32_e32 v86, v0
	v_mov_b32_e32 v87, v0
	v_mov_b32_e32 v88, v0
	v_mov_b32_e32 v89, v0
	v_mov_b32_e32 v98, v0
	v_mov_b32_e32 v99, v0
	v_mov_b32_e32 v100, v0
	v_mov_b32_e32 v101, v0
	v_mov_b32_e32 v102, v0
	v_mov_b32_e32 v103, v0
	v_mov_b32_e32 v104, v0
	v_mov_b32_e32 v105, v0
	v_mov_b32_e32 v114, v0
	v_mov_b32_e32 v115, v0
	v_mov_b32_e32 v116, v0
	v_mov_b32_e32 v117, v0
	v_mov_b32_e32 v118, v0
	v_mov_b32_e32 v119, v0
	v_mov_b32_e32 v120, v0
	v_mov_b32_e32 v121, v0
	v_mov_b32_e32 v74, v0
	v_mov_b32_e32 v75, v0
	v_mov_b32_e32 v76, v0
	v_mov_b32_e32 v77, v0
	v_mov_b32_e32 v78, v0
	v_mov_b32_e32 v79, v0
	v_mov_b32_e32 v80, v0
	v_mov_b32_e32 v81, v0
	v_mov_b32_e32 v90, v0
	v_mov_b32_e32 v91, v0
	v_mov_b32_e32 v92, v0
	v_mov_b32_e32 v93, v0
	v_mov_b32_e32 v94, v0
	v_mov_b32_e32 v95, v0
	v_mov_b32_e32 v96, v0
	v_mov_b32_e32 v97, v0
	v_mov_b32_e32 v106, v0
	v_mov_b32_e32 v107, v0
	v_mov_b32_e32 v108, v0
	v_mov_b32_e32 v109, v0
	v_mov_b32_e32 v110, v0
	v_mov_b32_e32 v111, v0
	v_mov_b32_e32 v112, v0
	v_mov_b32_e32 v113, v0
	v_mov_b32_e32 v122, v0
	v_mov_b32_e32 v123, v0
	v_mov_b32_e32 v124, v0
	v_mov_b32_e32 v125, v0
	v_mov_b32_e32 v126, v0
	v_mov_b32_e32 v127, v0
	v_mov_b32_e32 v128, v0
	v_mov_b32_e32 v129, v0
	v_add_u32_e32 v248, 0x10000, v242
.LBB0_755:
	s_add_u32 s6, s4, 0x100
	s_addc_u32 s7, s5, 0
	s_add_i32 s52, 0, 0x10000
	s_cmpk_eq_i32 s51, 0x54
	s_cselect_b32 s29, s23, s7
	s_cselect_b32 s28, s22, s6
	s_cselect_b32 s31, s27, s50
	s_cselect_b32 s30, s26, s33
	s_add_i32 s53, 0, 0x14000
	ds_read_b128 v[130:133], v248
	ds_read_b128 v[134:137], v248 offset:1024
	ds_read_b128 v[138:141], v248 offset:2048
	ds_read_b128 v[142:145], v248 offset:3072
	ds_read_b128 v[146:149], v248 offset:16384
	ds_read_b128 v[150:153], v248 offset:17408
	ds_read_b128 v[154:157], v248 offset:18432
	ds_read_b128 v[158:161], v248 offset:19456
	s_add_i32 m0, s36, 0xc000
	ds_read_b128 v[162:165], v243
	ds_read_b128 v[166:169], v243 offset:1024
	ds_read_b128 v[170:173], v243 offset:2048
	ds_read_b128 v[174:177], v243 offset:3072
	ds_read_b128 v[178:181], v243 offset:4096
	ds_read_b128 v[182:185], v243 offset:5120
	ds_read_b128 v[186:189], v243 offset:6144
	ds_read_b128 v[190:193], v243 offset:7168
	global_load_lds_dwordx4 v202, s[4:5]
	s_add_i32 m0, s36, 0xe000
	s_nop 0
	global_load_lds_dwordx4 v204, s[4:5]
	s_waitcnt vmcnt(8)
	s_waitcnt lgkmcnt(0)
	s_barrier
	s_setprio 1
	v_mfma_f32_16x16x32_bf16 v[126:129], v[130:133], v[162:165], v[126:129]
	v_mfma_f32_16x16x32_bf16 v[126:129], v[134:137], v[166:169], v[126:129]
	v_mfma_f32_16x16x32_bf16 v[122:125], v[142:145], v[166:169], v[122:125]
	v_mfma_f32_16x16x32_bf16 v[122:125], v[138:141], v[162:165], v[122:125]
	v_mfma_f32_16x16x32_bf16 v[106:109], v[138:141], v[170:173], v[106:109]
	v_mfma_f32_16x16x32_bf16 v[106:109], v[142:145], v[174:177], v[106:109]
	v_mfma_f32_16x16x32_bf16 v[110:113], v[134:137], v[174:177], v[110:113]
	v_mfma_f32_16x16x32_bf16 v[110:113], v[130:133], v[170:173], v[110:113]
	v_mfma_f32_16x16x32_bf16 v[94:97], v[130:133], v[178:181], v[94:97]
	v_mfma_f32_16x16x32_bf16 v[94:97], v[134:137], v[182:185], v[94:97]
	v_mfma_f32_16x16x32_bf16 v[90:93], v[142:145], v[182:185], v[90:93]
	v_mfma_f32_16x16x32_bf16 v[90:93], v[138:141], v[178:181], v[90:93]
	v_mfma_f32_16x16x32_bf16 v[74:77], v[138:141], v[186:189], v[74:77]
	v_mfma_f32_16x16x32_bf16 v[74:77], v[142:145], v[190:193], v[74:77]
	v_mfma_f32_16x16x32_bf16 v[78:81], v[134:137], v[190:193], v[78:81]
	v_mfma_f32_16x16x32_bf16 v[78:81], v[130:133], v[186:189], v[78:81]
	v_mfma_f32_16x16x32_bf16 v[118:121], v[146:149], v[162:165], v[118:121]
	v_mfma_f32_16x16x32_bf16 v[118:121], v[150:153], v[166:169], v[118:121]
	v_mfma_f32_16x16x32_bf16 v[114:117], v[158:161], v[166:169], v[114:117]
	v_mfma_f32_16x16x32_bf16 v[114:117], v[154:157], v[162:165], v[114:117]
	v_mfma_f32_16x16x32_bf16 v[98:101], v[154:157], v[170:173], v[98:101]
	v_mfma_f32_16x16x32_bf16 v[98:101], v[158:161], v[174:177], v[98:101]
	v_mfma_f32_16x16x32_bf16 v[102:105], v[150:153], v[174:177], v[102:105]
	v_mfma_f32_16x16x32_bf16 v[102:105], v[146:149], v[170:173], v[102:105]
	v_mfma_f32_16x16x32_bf16 v[86:89], v[146:149], v[178:181], v[86:89]
	v_mfma_f32_16x16x32_bf16 v[86:89], v[150:153], v[182:185], v[86:89]
	v_mfma_f32_16x16x32_bf16 v[82:85], v[158:161], v[182:185], v[82:85]
	v_mfma_f32_16x16x32_bf16 v[82:85], v[154:157], v[178:181], v[82:85]
	v_mfma_f32_16x16x32_bf16 v[66:69], v[154:157], v[186:189], v[66:69]
	v_mfma_f32_16x16x32_bf16 v[66:69], v[158:161], v[190:193], v[66:69]
	v_mfma_f32_16x16x32_bf16 v[70:73], v[150:153], v[190:193], v[70:73]
	v_mfma_f32_16x16x32_bf16 v[70:73], v[146:149], v[186:189], v[70:73]
	s_setprio 0
	s_barrier
	s_add_i32 s4, s52, s1
	v_lshl_add_u64 v[194:195], s[30:31], 0, v[32:33]
	s_mov_b32 m0, s4
	ds_read_b128 v[162:165], v243 offset:16384
	ds_read_b128 v[166:169], v243 offset:17408
	ds_read_b128 v[170:173], v243 offset:18432
	ds_read_b128 v[174:177], v243 offset:19456
	ds_read_b128 v[178:181], v243 offset:20480
	ds_read_b128 v[182:185], v243 offset:21504
	ds_read_b128 v[186:189], v243 offset:22528
	ds_read_b128 v[190:193], v243 offset:23552
	global_load_lds_dwordx4 v[194:195], off
	s_add_i32 m0, s4, 0x2000
	s_add_u32 s4, s30, 0x160000
	v_lshl_add_u64 v[206:207], s[30:31], 0, v[200:201]
	s_addc_u32 s5, s31, 0
	s_add_i32 s52, s53, s1
	global_load_lds_dwordx4 v[206:207], off
	s_mov_b32 m0, s52
	v_lshl_add_u64 v[210:211], s[28:29], 0, v[198:199]
	global_load_lds_dwordx4 v32, s[4:5]
	s_add_i32 m0, s52, 0x2000
	s_nop 0
	global_load_lds_dwordx4 v200, s[4:5]
	v_lshl_add_u64 v[208:209], s[28:29], 0, v[196:197]
	s_mov_b32 m0, s36
	s_nop 0
	global_load_lds_dwordx4 v[208:209], off
	s_mov_b32 m0, s38
	s_nop 0
	global_load_lds_dwordx4 v[210:211], off
	s_waitcnt vmcnt(8)
	s_waitcnt lgkmcnt(0)
	s_barrier
	s_setprio 1
	v_mfma_f32_16x16x32_bf16 v[62:65], v[130:133], v[162:165], v[62:65]
	v_mfma_f32_16x16x32_bf16 v[62:65], v[134:137], v[166:169], v[62:65]
	v_mfma_f32_16x16x32_bf16 v[58:61], v[142:145], v[166:169], v[58:61]
	v_mfma_f32_16x16x32_bf16 v[58:61], v[138:141], v[162:165], v[58:61]
	v_mfma_f32_16x16x32_bf16 v[42:45], v[138:141], v[170:173], v[42:45]
	v_mfma_f32_16x16x32_bf16 v[42:45], v[142:145], v[174:177], v[42:45]
	v_mfma_f32_16x16x32_bf16 v[46:49], v[134:137], v[174:177], v[46:49]
	v_mfma_f32_16x16x32_bf16 v[46:49], v[130:133], v[170:173], v[46:49]
	v_mfma_f32_16x16x32_bf16 v[28:31], v[130:133], v[178:181], v[28:31]
	v_mfma_f32_16x16x32_bf16 v[28:31], v[134:137], v[182:185], v[28:31]
	v_mfma_f32_16x16x32_bf16 v[24:27], v[142:145], v[182:185], v[24:27]
	v_mfma_f32_16x16x32_bf16 v[24:27], v[138:141], v[178:181], v[24:27]
	v_mfma_f32_16x16x32_bf16 v[8:11], v[138:141], v[186:189], v[8:11]
	v_mfma_f32_16x16x32_bf16 v[8:11], v[142:145], v[190:193], v[8:11]
	v_mfma_f32_16x16x32_bf16 v[12:15], v[134:137], v[190:193], v[12:15]
	v_mfma_f32_16x16x32_bf16 v[12:15], v[130:133], v[186:189], v[12:15]
	v_mfma_f32_16x16x32_bf16 v[54:57], v[146:149], v[162:165], v[54:57]
	v_mfma_f32_16x16x32_bf16 v[54:57], v[150:153], v[166:169], v[54:57]
	v_mfma_f32_16x16x32_bf16 v[50:53], v[158:161], v[166:169], v[50:53]
	v_mfma_f32_16x16x32_bf16 v[50:53], v[154:157], v[162:165], v[50:53]
	v_mfma_f32_16x16x32_bf16 v[34:37], v[154:157], v[170:173], v[34:37]
	v_mfma_f32_16x16x32_bf16 v[34:37], v[158:161], v[174:177], v[34:37]
	v_mfma_f32_16x16x32_bf16 v[38:41], v[150:153], v[174:177], v[38:41]
	v_mfma_f32_16x16x32_bf16 v[38:41], v[146:149], v[170:173], v[38:41]
	v_mfma_f32_16x16x32_bf16 v[20:23], v[146:149], v[178:181], v[20:23]
	v_mfma_f32_16x16x32_bf16 v[20:23], v[150:153], v[182:185], v[20:23]
	v_mfma_f32_16x16x32_bf16 v[16:19], v[158:161], v[182:185], v[16:19]
	v_mfma_f32_16x16x32_bf16 v[16:19], v[154:157], v[178:181], v[16:19]
	v_mfma_f32_16x16x32_bf16 v[0:3], v[154:157], v[186:189], v[0:3]
	v_mfma_f32_16x16x32_bf16 v[0:3], v[158:161], v[190:193], v[0:3]
	v_mfma_f32_16x16x32_bf16 v[4:7], v[150:153], v[190:193], v[4:7]
	v_mfma_f32_16x16x32_bf16 v[4:7], v[146:149], v[186:189], v[4:7]
	s_setprio 0
	s_barrier
	s_add_i32 s52, 0, 0x18000
	s_add_i32 s53, 0, 0x1c000
	ds_read_b128 v[130:133], v248 offset:32768
	ds_read_b128 v[134:137], v248 offset:33792
	ds_read_b128 v[138:141], v248 offset:34816
	ds_read_b128 v[142:145], v248 offset:35840
	ds_read_b128 v[146:149], v248 offset:49152
	ds_read_b128 v[150:153], v248 offset:50176
	ds_read_b128 v[154:157], v248 offset:51200
	ds_read_b128 v[158:161], v248 offset:52224
	s_add_u32 s4, s28, 0x160000
	s_addc_u32 s5, s29, 0
	s_mov_b32 m0, s39
	ds_read_b128 v[162:165], v243 offset:32768
	ds_read_b128 v[166:169], v243 offset:33792
	ds_read_b128 v[170:173], v243 offset:34816
	ds_read_b128 v[174:177], v243 offset:35840
	ds_read_b128 v[178:181], v243 offset:36864
	ds_read_b128 v[182:185], v243 offset:37888
	ds_read_b128 v[186:189], v243 offset:38912
	ds_read_b128 v[190:193], v243 offset:39936
	global_load_lds_dwordx4 v196, s[4:5]
	s_mov_b32 m0, s42
	s_nop 0
	global_load_lds_dwordx4 v198, s[4:5]
	s_waitcnt vmcnt(8)
	s_waitcnt lgkmcnt(0)
	s_barrier
	s_setprio 1
	v_mfma_f32_16x16x32_bf16 v[126:129], v[130:133], v[162:165], v[126:129]
	v_mfma_f32_16x16x32_bf16 v[126:129], v[134:137], v[166:169], v[126:129]
	v_mfma_f32_16x16x32_bf16 v[122:125], v[142:145], v[166:169], v[122:125]
	v_mfma_f32_16x16x32_bf16 v[122:125], v[138:141], v[162:165], v[122:125]
	v_mfma_f32_16x16x32_bf16 v[106:109], v[138:141], v[170:173], v[106:109]
	v_mfma_f32_16x16x32_bf16 v[106:109], v[142:145], v[174:177], v[106:109]
	v_mfma_f32_16x16x32_bf16 v[110:113], v[134:137], v[174:177], v[110:113]
	v_mfma_f32_16x16x32_bf16 v[110:113], v[130:133], v[170:173], v[110:113]
	v_mfma_f32_16x16x32_bf16 v[94:97], v[130:133], v[178:181], v[94:97]
	v_mfma_f32_16x16x32_bf16 v[94:97], v[134:137], v[182:185], v[94:97]
	v_mfma_f32_16x16x32_bf16 v[90:93], v[142:145], v[182:185], v[90:93]
	v_mfma_f32_16x16x32_bf16 v[90:93], v[138:141], v[178:181], v[90:93]
	v_mfma_f32_16x16x32_bf16 v[74:77], v[138:141], v[186:189], v[74:77]
	v_mfma_f32_16x16x32_bf16 v[74:77], v[142:145], v[190:193], v[74:77]
	v_mfma_f32_16x16x32_bf16 v[78:81], v[134:137], v[190:193], v[78:81]
	v_mfma_f32_16x16x32_bf16 v[78:81], v[130:133], v[186:189], v[78:81]
	v_mfma_f32_16x16x32_bf16 v[118:121], v[146:149], v[162:165], v[118:121]
	v_mfma_f32_16x16x32_bf16 v[118:121], v[150:153], v[166:169], v[118:121]
	v_mfma_f32_16x16x32_bf16 v[114:117], v[158:161], v[166:169], v[114:117]
	v_mfma_f32_16x16x32_bf16 v[114:117], v[154:157], v[162:165], v[114:117]
	v_mfma_f32_16x16x32_bf16 v[98:101], v[154:157], v[170:173], v[98:101]
	v_mfma_f32_16x16x32_bf16 v[98:101], v[158:161], v[174:177], v[98:101]
	v_mfma_f32_16x16x32_bf16 v[102:105], v[150:153], v[174:177], v[102:105]
	v_mfma_f32_16x16x32_bf16 v[102:105], v[146:149], v[170:173], v[102:105]
	v_mfma_f32_16x16x32_bf16 v[86:89], v[146:149], v[178:181], v[86:89]
	v_mfma_f32_16x16x32_bf16 v[86:89], v[150:153], v[182:185], v[86:89]
	v_mfma_f32_16x16x32_bf16 v[82:85], v[158:161], v[182:185], v[82:85]
	v_mfma_f32_16x16x32_bf16 v[82:85], v[154:157], v[178:181], v[82:85]
	v_mfma_f32_16x16x32_bf16 v[66:69], v[154:157], v[186:189], v[66:69]
	v_mfma_f32_16x16x32_bf16 v[66:69], v[158:161], v[190:193], v[66:69]
	v_mfma_f32_16x16x32_bf16 v[70:73], v[150:153], v[190:193], v[70:73]
	v_mfma_f32_16x16x32_bf16 v[70:73], v[146:149], v[186:189], v[70:73]
	s_setprio 0
	s_barrier
	s_add_i32 s4, s52, s1
	v_lshl_add_u64 v[194:195], v[194:195], 0, s[34:35]
	s_mov_b32 m0, s4
	ds_read_b128 v[162:165], v243 offset:49152
	ds_read_b128 v[166:169], v243 offset:50176
	ds_read_b128 v[170:173], v243 offset:51200
	ds_read_b128 v[174:177], v243 offset:52224
	ds_read_b128 v[178:181], v243 offset:53248
	ds_read_b128 v[182:185], v243 offset:54272
	ds_read_b128 v[186:189], v243 offset:55296
	ds_read_b128 v[190:193], v243 offset:56320
	global_load_lds_dwordx4 v[194:195], off
	s_add_i32 m0, s4, 0x2000
	s_add_u32 s4, s30, 0x160080
	v_lshl_add_u64 v[194:195], v[206:207], 0, s[34:35]
	s_addc_u32 s5, s31, 0
	s_add_i32 s28, s53, s1
	global_load_lds_dwordx4 v[194:195], off
	s_mov_b32 m0, s28
	s_nop 0
	global_load_lds_dwordx4 v32, s[4:5]
	s_add_i32 m0, s28, 0x2000
	s_nop 0
	global_load_lds_dwordx4 v200, s[4:5]
	v_lshl_add_u64 v[194:195], v[208:209], 0, s[34:35]
	s_mov_b32 m0, s44
	s_nop 0
	global_load_lds_dwordx4 v[194:195], off
	v_lshl_add_u64 v[194:195], v[210:211], 0, s[34:35]
	s_mov_b32 m0, s45
	s_nop 0
	global_load_lds_dwordx4 v[194:195], off
	s_waitcnt vmcnt(8)
	s_waitcnt lgkmcnt(0)
	s_barrier
	s_setprio 1
	v_mfma_f32_16x16x32_bf16 v[62:65], v[130:133], v[162:165], v[62:65]
	v_mfma_f32_16x16x32_bf16 v[62:65], v[134:137], v[166:169], v[62:65]
	v_mfma_f32_16x16x32_bf16 v[58:61], v[142:145], v[166:169], v[58:61]
	v_mfma_f32_16x16x32_bf16 v[58:61], v[138:141], v[162:165], v[58:61]
	v_mfma_f32_16x16x32_bf16 v[42:45], v[138:141], v[170:173], v[42:45]
	v_mfma_f32_16x16x32_bf16 v[42:45], v[142:145], v[174:177], v[42:45]
	v_mfma_f32_16x16x32_bf16 v[46:49], v[134:137], v[174:177], v[46:49]
	v_mfma_f32_16x16x32_bf16 v[46:49], v[130:133], v[170:173], v[46:49]
	v_mfma_f32_16x16x32_bf16 v[28:31], v[130:133], v[178:181], v[28:31]
	v_mfma_f32_16x16x32_bf16 v[28:31], v[134:137], v[182:185], v[28:31]
	v_mfma_f32_16x16x32_bf16 v[24:27], v[142:145], v[182:185], v[24:27]
	v_mfma_f32_16x16x32_bf16 v[24:27], v[138:141], v[178:181], v[24:27]
	v_mfma_f32_16x16x32_bf16 v[8:11], v[138:141], v[186:189], v[8:11]
	v_mfma_f32_16x16x32_bf16 v[8:11], v[142:145], v[190:193], v[8:11]
	v_mfma_f32_16x16x32_bf16 v[12:15], v[134:137], v[190:193], v[12:15]
	v_mfma_f32_16x16x32_bf16 v[12:15], v[130:133], v[186:189], v[12:15]
	v_mfma_f32_16x16x32_bf16 v[54:57], v[146:149], v[162:165], v[54:57]
	v_mfma_f32_16x16x32_bf16 v[54:57], v[150:153], v[166:169], v[54:57]
	v_mfma_f32_16x16x32_bf16 v[50:53], v[158:161], v[166:169], v[50:53]
	v_mfma_f32_16x16x32_bf16 v[50:53], v[154:157], v[162:165], v[50:53]
	v_mfma_f32_16x16x32_bf16 v[34:37], v[154:157], v[170:173], v[34:37]
	v_mfma_f32_16x16x32_bf16 v[34:37], v[158:161], v[174:177], v[34:37]
	v_mfma_f32_16x16x32_bf16 v[38:41], v[150:153], v[174:177], v[38:41]
	v_mfma_f32_16x16x32_bf16 v[38:41], v[146:149], v[170:173], v[38:41]
	v_mfma_f32_16x16x32_bf16 v[20:23], v[146:149], v[178:181], v[20:23]
	v_mfma_f32_16x16x32_bf16 v[20:23], v[150:153], v[182:185], v[20:23]
	v_mfma_f32_16x16x32_bf16 v[16:19], v[158:161], v[182:185], v[16:19]
	v_mfma_f32_16x16x32_bf16 v[16:19], v[154:157], v[178:181], v[16:19]
	v_mfma_f32_16x16x32_bf16 v[0:3], v[154:157], v[186:189], v[0:3]
	v_mfma_f32_16x16x32_bf16 v[0:3], v[158:161], v[190:193], v[0:3]
	v_mfma_f32_16x16x32_bf16 v[4:7], v[150:153], v[190:193], v[4:7]
	v_mfma_f32_16x16x32_bf16 v[4:7], v[146:149], v[186:189], v[4:7]
	s_setprio 0
	s_barrier
	s_add_i32 s51, s51, 2
	s_add_u32 s33, s33, 0x100
	s_addc_u32 s50, s50, 0
	s_cmpk_gt_u32 s51, 0x55
	s_mov_b64 s[4:5], s[6:7]
	s_cbranch_scc0 .LBB0_755
	s_and_b64 vcc, exec, s[18:19]
	s_cbranch_vccz .LBB0_758
	s_barrier

.LBB0_887:
	s_add_u32 s50, s30, 0x100
	s_addc_u32 s51, s31, 0
	s_ashr_i32 s21, s20, 31
	s_lshl_b64 s[26:27], s[20:21], 20
	s_add_u32 s26, s10, s26
	s_addc_u32 s27, s11, s27
	s_and_b64 s[38:39], s[38:39], exec
	s_cselect_b32 s21, s27, s31
	s_cselect_b32 s52, s26, s30
	s_add_u32 s30, s16, 0x80080
	s_addc_u32 s31, s17, 0
	v_lshl_add_u64 v[130:131], s[30:31], 0, v[168:169]
	v_lshl_add_u64 v[132:133], s[30:31], 0, v[170:171]
	s_mov_b32 s53, -2
	s_mov_b64 s[30:31], 0
	v_add_u32_e32 v224, 0x10000, v178
.LBB0_888:
	s_add_u32 s38, s16, s30
	s_addc_u32 s39, s17, s31
	s_add_u32 s38, s38, 0x100
	s_addc_u32 s39, s39, 0
	s_add_u32 s54, s50, s30
	s_addc_u32 s55, s51, s31
	s_add_i32 s56, 0, 0x10000
	s_cmpk_eq_i32 s30, 0xf00
	s_cselect_b32 s41, s29, s39
	s_cselect_b32 s40, s28, s38
	s_cselect_b32 s39, s21, s55
	s_cselect_b32 s38, s52, s54
	s_add_i32 s57, 0, 0x14000
	ds_read_b128 v[134:137], v224
	ds_read_b128 v[138:141], v224 offset:1024
	ds_read_b128 v[142:145], v224 offset:2048
	ds_read_b128 v[146:149], v224 offset:3072
	ds_read_b128 v[150:153], v224 offset:16384
	ds_read_b128 v[154:157], v224 offset:17408
	ds_read_b128 v[158:161], v224 offset:18432
	ds_read_b128 v[172:175], v224 offset:19456
	v_lshl_add_u64 v[212:213], v[130:131], 0, s[30:31]
	s_add_i32 m0, s24, 0xc000
	ds_read_b128 v[180:183], v179
	ds_read_b128 v[184:187], v179 offset:1024
	ds_read_b128 v[188:191], v179 offset:2048
	ds_read_b128 v[192:195], v179 offset:3072
	ds_read_b128 v[196:199], v179 offset:4096
	ds_read_b128 v[200:203], v179 offset:5120
	ds_read_b128 v[204:207], v179 offset:6144
	ds_read_b128 v[208:211], v179 offset:7168
	global_load_lds_dwordx4 v[212:213], off
	v_lshl_add_u64 v[212:213], v[132:133], 0, s[30:31]
	s_add_i32 m0, s24, 0xe000
	s_nop 0
	global_load_lds_dwordx4 v[212:213], off
	s_waitcnt vmcnt(8)
	s_waitcnt lgkmcnt(0)
	s_barrier
	s_setprio 1
	v_mfma_f32_16x16x32_bf16 v[82:85], v[134:137], v[180:183], v[82:85]
	v_mfma_f32_16x16x32_bf16 v[82:85], v[138:141], v[184:187], v[82:85]
	v_mfma_f32_16x16x32_bf16 v[78:81], v[146:149], v[184:187], v[78:81]
	v_mfma_f32_16x16x32_bf16 v[78:81], v[142:145], v[180:183], v[78:81]
	v_mfma_f32_16x16x32_bf16 v[70:73], v[142:145], v[188:191], v[70:73]
	v_mfma_f32_16x16x32_bf16 v[70:73], v[146:149], v[192:195], v[70:73]
	v_mfma_f32_16x16x32_bf16 v[74:77], v[138:141], v[192:195], v[74:77]
	v_mfma_f32_16x16x32_bf16 v[74:77], v[134:137], v[188:191], v[74:77]
	v_mfma_f32_16x16x32_bf16 v[66:69], v[134:137], v[196:199], v[66:69]
	v_mfma_f32_16x16x32_bf16 v[66:69], v[138:141], v[200:203], v[66:69]
	v_mfma_f32_16x16x32_bf16 v[62:65], v[146:149], v[200:203], v[62:65]
	v_mfma_f32_16x16x32_bf16 v[62:65], v[142:145], v[196:199], v[62:65]
	v_mfma_f32_16x16x32_bf16 v[54:57], v[142:145], v[204:207], v[54:57]
	v_mfma_f32_16x16x32_bf16 v[54:57], v[146:149], v[208:211], v[54:57]
	v_mfma_f32_16x16x32_bf16 v[58:61], v[138:141], v[208:211], v[58:61]
	v_mfma_f32_16x16x32_bf16 v[58:61], v[134:137], v[204:207], v[58:61]
	v_mfma_f32_16x16x32_bf16 v[50:53], v[150:153], v[180:183], v[50:53]
	v_mfma_f32_16x16x32_bf16 v[50:53], v[154:157], v[184:187], v[50:53]
	v_mfma_f32_16x16x32_bf16 v[46:49], v[172:175], v[184:187], v[46:49]
	v_mfma_f32_16x16x32_bf16 v[46:49], v[158:161], v[180:183], v[46:49]
	v_mfma_f32_16x16x32_bf16 v[38:41], v[158:161], v[188:191], v[38:41]
	v_mfma_f32_16x16x32_bf16 v[38:41], v[172:175], v[192:195], v[38:41]
	v_mfma_f32_16x16x32_bf16 v[42:45], v[154:157], v[192:195], v[42:45]
	v_mfma_f32_16x16x32_bf16 v[42:45], v[150:153], v[188:191], v[42:45]
	v_mfma_f32_16x16x32_bf16 v[34:37], v[150:153], v[196:199], v[34:37]
	v_mfma_f32_16x16x32_bf16 v[34:37], v[154:157], v[200:203], v[34:37]
	v_mfma_f32_16x16x32_bf16 v[28:31], v[172:175], v[200:203], v[28:31]
	v_mfma_f32_16x16x32_bf16 v[28:31], v[158:161], v[196:199], v[28:31]
	v_mfma_f32_16x16x32_bf16 v[20:23], v[158:161], v[204:207], v[20:23]
	v_mfma_f32_16x16x32_bf16 v[20:23], v[172:175], v[208:211], v[20:23]
	v_mfma_f32_16x16x32_bf16 v[24:27], v[154:157], v[208:211], v[24:27]
	v_mfma_f32_16x16x32_bf16 v[24:27], v[150:153], v[204:207], v[24:27]
	s_setprio 0
	s_barrier
	s_add_i32 s54, s56, s13
	v_lshl_add_u64 v[212:213], s[38:39], 0, v[32:33]
	s_mov_b32 m0, s54
	ds_read_b128 v[180:183], v179 offset:16384
	ds_read_b128 v[184:187], v179 offset:17408
	ds_read_b128 v[188:191], v179 offset:18432
	ds_read_b128 v[192:195], v179 offset:19456
	ds_read_b128 v[196:199], v179 offset:20480
	ds_read_b128 v[200:203], v179 offset:21504
	ds_read_b128 v[204:207], v179 offset:22528
	ds_read_b128 v[208:211], v179 offset:23552
	global_load_lds_dwordx4 v[212:213], off
	s_add_i32 m0, s54, 0x2000
	s_add_u32 s54, s38, 0x80000
	v_lshl_add_u64 v[214:215], s[38:39], 0, v[166:167]
	s_addc_u32 s55, s39, 0
	s_add_i32 s56, s57, s13
	global_load_lds_dwordx4 v[214:215], off
	s_mov_b32 m0, s56
	v_lshl_add_u64 v[220:221], s[40:41], 0, v[164:165]
	global_load_lds_dwordx4 v32, s[54:55]
	s_add_i32 m0, s56, 0x2000
	s_nop 0
	global_load_lds_dwordx4 v166, s[54:55]
	v_lshl_add_u64 v[216:217], s[40:41], 0, v[162:163]
	s_mov_b32 m0, s24
	s_nop 0
	global_load_lds_dwordx4 v[216:217], off
	s_mov_b32 m0, s25
	s_nop 0
	global_load_lds_dwordx4 v[220:221], off
	s_waitcnt vmcnt(8)
	s_waitcnt lgkmcnt(0)
	s_barrier
	s_setprio 1
	v_mfma_f32_16x16x32_bf16 v[16:19], v[134:137], v[180:183], v[16:19]
	v_mfma_f32_16x16x32_bf16 v[16:19], v[138:141], v[184:187], v[16:19]
	v_mfma_f32_16x16x32_bf16 v[12:15], v[146:149], v[184:187], v[12:15]
	v_mfma_f32_16x16x32_bf16 v[12:15], v[142:145], v[180:183], v[12:15]
	v_mfma_f32_16x16x32_bf16 v[4:7], v[142:145], v[188:191], v[4:7]
	v_mfma_f32_16x16x32_bf16 v[4:7], v[146:149], v[192:195], v[4:7]
	v_mfma_f32_16x16x32_bf16 v[8:11], v[138:141], v[192:195], v[8:11]
	v_mfma_f32_16x16x32_bf16 v[8:11], v[134:137], v[188:191], v[8:11]
	v_mfma_f32_16x16x32_bf16 v[0:3], v[134:137], v[196:199], v[0:3]
	v_mfma_f32_16x16x32_bf16 v[0:3], v[138:141], v[200:203], v[0:3]
	v_mfma_f32_16x16x32_bf16 v[86:89], v[146:149], v[200:203], v[86:89]
	v_mfma_f32_16x16x32_bf16 v[86:89], v[142:145], v[196:199], v[86:89]
	v_mfma_f32_16x16x32_bf16 v[94:97], v[142:145], v[204:207], v[94:97]
	v_mfma_f32_16x16x32_bf16 v[94:97], v[146:149], v[208:211], v[94:97]
	v_mfma_f32_16x16x32_bf16 v[90:93], v[138:141], v[208:211], v[90:93]
	v_mfma_f32_16x16x32_bf16 v[90:93], v[134:137], v[204:207], v[90:93]
	v_mfma_f32_16x16x32_bf16 v[98:101], v[150:153], v[180:183], v[98:101]
	v_mfma_f32_16x16x32_bf16 v[98:101], v[154:157], v[184:187], v[98:101]
	v_mfma_f32_16x16x32_bf16 v[102:105], v[172:175], v[184:187], v[102:105]
	v_mfma_f32_16x16x32_bf16 v[102:105], v[158:161], v[180:183], v[102:105]
	v_mfma_f32_16x16x32_bf16 v[110:113], v[158:161], v[188:191], v[110:113]
	v_mfma_f32_16x16x32_bf16 v[110:113], v[172:175], v[192:195], v[110:113]
	v_mfma_f32_16x16x32_bf16 v[106:109], v[154:157], v[192:195], v[106:109]
	v_mfma_f32_16x16x32_bf16 v[106:109], v[150:153], v[188:191], v[106:109]
	v_mfma_f32_16x16x32_bf16 v[114:117], v[150:153], v[196:199], v[114:117]
	v_mfma_f32_16x16x32_bf16 v[114:117], v[154:157], v[200:203], v[114:117]
	v_mfma_f32_16x16x32_bf16 v[118:121], v[172:175], v[200:203], v[118:121]
	v_mfma_f32_16x16x32_bf16 v[118:121], v[158:161], v[196:199], v[118:121]
	v_mfma_f32_16x16x32_bf16 v[126:129], v[158:161], v[204:207], v[126:129]
	v_mfma_f32_16x16x32_bf16 v[126:129], v[172:175], v[208:211], v[126:129]
	v_mfma_f32_16x16x32_bf16 v[122:125], v[154:157], v[208:211], v[122:125]
	v_mfma_f32_16x16x32_bf16 v[122:125], v[150:153], v[204:207], v[122:125]
	s_setprio 0
	s_barrier
	s_add_i32 s54, 0, 0x18000
	s_add_i32 s55, 0, 0x1c000
	ds_read_b128 v[134:137], v224 offset:32768
	ds_read_b128 v[138:141], v224 offset:33792
	ds_read_b128 v[142:145], v224 offset:34816
	ds_read_b128 v[146:149], v224 offset:35840
	ds_read_b128 v[150:153], v224 offset:49152
	ds_read_b128 v[154:157], v224 offset:50176
	ds_read_b128 v[158:161], v224 offset:51200
	ds_read_b128 v[172:175], v224 offset:52224
	s_add_u32 s40, s40, 0x80000
	s_addc_u32 s41, s41, 0
	s_mov_b32 m0, s33
	ds_read_b128 v[180:183], v179 offset:32768
	ds_read_b128 v[184:187], v179 offset:33792
	ds_read_b128 v[188:191], v179 offset:34816
	ds_read_b128 v[192:195], v179 offset:35840
	ds_read_b128 v[196:199], v179 offset:36864
	ds_read_b128 v[200:203], v179 offset:37888
	ds_read_b128 v[204:207], v179 offset:38912
	ds_read_b128 v[208:211], v179 offset:39936
	global_load_lds_dwordx4 v162, s[40:41]
	s_mov_b32 m0, s36
	s_nop 0
	global_load_lds_dwordx4 v164, s[40:41]
	s_waitcnt vmcnt(8)
	s_waitcnt lgkmcnt(0)
	s_barrier
	s_setprio 1
	v_mfma_f32_16x16x32_bf16 v[82:85], v[134:137], v[180:183], v[82:85]
	v_mfma_f32_16x16x32_bf16 v[82:85], v[138:141], v[184:187], v[82:85]
	v_mfma_f32_16x16x32_bf16 v[78:81], v[146:149], v[184:187], v[78:81]
	v_mfma_f32_16x16x32_bf16 v[78:81], v[142:145], v[180:183], v[78:81]
	v_mfma_f32_16x16x32_bf16 v[70:73], v[142:145], v[188:191], v[70:73]
	v_mfma_f32_16x16x32_bf16 v[70:73], v[146:149], v[192:195], v[70:73]
	v_mfma_f32_16x16x32_bf16 v[74:77], v[138:141], v[192:195], v[74:77]
	v_mfma_f32_16x16x32_bf16 v[74:77], v[134:137], v[188:191], v[74:77]
	v_mfma_f32_16x16x32_bf16 v[66:69], v[134:137], v[196:199], v[66:69]
	v_mfma_f32_16x16x32_bf16 v[66:69], v[138:141], v[200:203], v[66:69]
	v_mfma_f32_16x16x32_bf16 v[62:65], v[146:149], v[200:203], v[62:65]
	v_mfma_f32_16x16x32_bf16 v[62:65], v[142:145], v[196:199], v[62:65]
	v_mfma_f32_16x16x32_bf16 v[54:57], v[142:145], v[204:207], v[54:57]
	v_mfma_f32_16x16x32_bf16 v[54:57], v[146:149], v[208:211], v[54:57]
	v_mfma_f32_16x16x32_bf16 v[58:61], v[138:141], v[208:211], v[58:61]
	v_mfma_f32_16x16x32_bf16 v[58:61], v[134:137], v[204:207], v[58:61]
	v_mfma_f32_16x16x32_bf16 v[50:53], v[150:153], v[180:183], v[50:53]
	v_mfma_f32_16x16x32_bf16 v[50:53], v[154:157], v[184:187], v[50:53]
	v_mfma_f32_16x16x32_bf16 v[46:49], v[172:175], v[184:187], v[46:49]
	v_mfma_f32_16x16x32_bf16 v[46:49], v[158:161], v[180:183], v[46:49]
	v_mfma_f32_16x16x32_bf16 v[38:41], v[158:161], v[188:191], v[38:41]
	v_mfma_f32_16x16x32_bf16 v[38:41], v[172:175], v[192:195], v[38:41]
	v_mfma_f32_16x16x32_bf16 v[42:45], v[154:157], v[192:195], v[42:45]
	v_mfma_f32_16x16x32_bf16 v[42:45], v[150:153], v[188:191], v[42:45]
	v_mfma_f32_16x16x32_bf16 v[34:37], v[150:153], v[196:199], v[34:37]
	v_mfma_f32_16x16x32_bf16 v[34:37], v[154:157], v[200:203], v[34:37]
	v_mfma_f32_16x16x32_bf16 v[28:31], v[172:175], v[200:203], v[28:31]
	v_mfma_f32_16x16x32_bf16 v[28:31], v[158:161], v[196:199], v[28:31]
	v_mfma_f32_16x16x32_bf16 v[20:23], v[158:161], v[204:207], v[20:23]
	v_mfma_f32_16x16x32_bf16 v[20:23], v[172:175], v[208:211], v[20:23]
	v_mfma_f32_16x16x32_bf16 v[24:27], v[154:157], v[208:211], v[24:27]
	v_mfma_f32_16x16x32_bf16 v[24:27], v[150:153], v[204:207], v[24:27]
	s_setprio 0
	s_barrier
	s_add_i32 s40, s54, s13
	v_lshl_add_u64 v[212:213], v[212:213], 0, s[34:35]
	s_mov_b32 m0, s40
	ds_read_b128 v[180:183], v179 offset:49152
	ds_read_b128 v[184:187], v179 offset:50176
	ds_read_b128 v[188:191], v179 offset:51200
	ds_read_b128 v[192:195], v179 offset:52224
	ds_read_b128 v[196:199], v179 offset:53248
	ds_read_b128 v[200:203], v179 offset:54272
	ds_read_b128 v[204:207], v179 offset:55296
	ds_read_b128 v[208:211], v179 offset:56320
	global_load_lds_dwordx4 v[212:213], off
	s_add_i32 m0, s40, 0x2000
	s_add_u32 s38, s38, 0x80080
	v_lshl_add_u64 v[212:213], v[214:215], 0, s[34:35]
	s_addc_u32 s39, s39, 0
	s_add_i32 s40, s55, s13
	global_load_lds_dwordx4 v[212:213], off
	s_mov_b32 m0, s40
	s_nop 0
	global_load_lds_dwordx4 v32, s[38:39]
	s_add_i32 m0, s40, 0x2000
	s_nop 0
	global_load_lds_dwordx4 v166, s[38:39]
	v_lshl_add_u64 v[212:213], v[216:217], 0, s[34:35]
	s_mov_b32 m0, s43
	s_nop 0
	global_load_lds_dwordx4 v[212:213], off
	v_lshl_add_u64 v[212:213], v[220:221], 0, s[34:35]
	s_mov_b32 m0, s44
	s_nop 0
	global_load_lds_dwordx4 v[212:213], off
	s_waitcnt vmcnt(8)
	s_waitcnt lgkmcnt(0)
	s_barrier
	s_setprio 1
	v_mfma_f32_16x16x32_bf16 v[16:19], v[134:137], v[180:183], v[16:19]
	v_mfma_f32_16x16x32_bf16 v[16:19], v[138:141], v[184:187], v[16:19]
	v_mfma_f32_16x16x32_bf16 v[12:15], v[146:149], v[184:187], v[12:15]
	v_mfma_f32_16x16x32_bf16 v[12:15], v[142:145], v[180:183], v[12:15]
	v_mfma_f32_16x16x32_bf16 v[4:7], v[142:145], v[188:191], v[4:7]
	v_mfma_f32_16x16x32_bf16 v[4:7], v[146:149], v[192:195], v[4:7]
	v_mfma_f32_16x16x32_bf16 v[8:11], v[138:141], v[192:195], v[8:11]
	v_mfma_f32_16x16x32_bf16 v[8:11], v[134:137], v[188:191], v[8:11]
	v_mfma_f32_16x16x32_bf16 v[0:3], v[134:137], v[196:199], v[0:3]
	v_mfma_f32_16x16x32_bf16 v[0:3], v[138:141], v[200:203], v[0:3]
	v_mfma_f32_16x16x32_bf16 v[86:89], v[146:149], v[200:203], v[86:89]
	v_mfma_f32_16x16x32_bf16 v[86:89], v[142:145], v[196:199], v[86:89]
	v_mfma_f32_16x16x32_bf16 v[94:97], v[142:145], v[204:207], v[94:97]
	v_mfma_f32_16x16x32_bf16 v[94:97], v[146:149], v[208:211], v[94:97]
	v_mfma_f32_16x16x32_bf16 v[90:93], v[138:141], v[208:211], v[90:93]
	v_mfma_f32_16x16x32_bf16 v[90:93], v[134:137], v[204:207], v[90:93]
	v_mfma_f32_16x16x32_bf16 v[98:101], v[150:153], v[180:183], v[98:101]
	v_mfma_f32_16x16x32_bf16 v[98:101], v[154:157], v[184:187], v[98:101]
	v_mfma_f32_16x16x32_bf16 v[102:105], v[172:175], v[184:187], v[102:105]
	v_mfma_f32_16x16x32_bf16 v[102:105], v[158:161], v[180:183], v[102:105]
	v_mfma_f32_16x16x32_bf16 v[110:113], v[158:161], v[188:191], v[110:113]
	v_mfma_f32_16x16x32_bf16 v[110:113], v[172:175], v[192:195], v[110:113]
	v_mfma_f32_16x16x32_bf16 v[106:109], v[154:157], v[192:195], v[106:109]
	v_mfma_f32_16x16x32_bf16 v[106:109], v[150:153], v[188:191], v[106:109]
	v_mfma_f32_16x16x32_bf16 v[114:117], v[150:153], v[196:199], v[114:117]
	v_mfma_f32_16x16x32_bf16 v[114:117], v[154:157], v[200:203], v[114:117]
	v_mfma_f32_16x16x32_bf16 v[118:121], v[172:175], v[200:203], v[118:121]
	v_mfma_f32_16x16x32_bf16 v[118:121], v[158:161], v[196:199], v[118:121]
	v_mfma_f32_16x16x32_bf16 v[126:129], v[158:161], v[204:207], v[126:129]
	v_mfma_f32_16x16x32_bf16 v[126:129], v[172:175], v[208:211], v[126:129]
	v_mfma_f32_16x16x32_bf16 v[122:125], v[154:157], v[208:211], v[122:125]
	v_mfma_f32_16x16x32_bf16 v[122:125], v[150:153], v[204:207], v[122:125]
	s_setprio 0
	s_barrier
	s_add_i32 s53, s53, 2
	s_add_u32 s30, s30, 0x100
	s_addc_u32 s31, s31, 0
	s_cmp_gt_u32 s53, 29
	s_cbranch_scc0 .LBB0_888
	s_and_b64 vcc, exec, s[18:19]
	s_cbranch_vccz .LBB0_891
	s_barrier
